# Y-GEMM gelu epilogue rewritten with packed f32 ops (same operation order), on top of GLU epilogue rewrite and batched attention staging
# speedup vs baseline: 1.0151x; 1.0022x over previous
; __device__ __forceinline__ unsigned cvt_pk_bf16(float lo, float hi) { const f32x2_t v = {lo, hi}; const bf16x2_t b = __builtin_convertvector(v, bf16x2_t); return __builtin_bit_cast(unsigned, b); }
; __device__ __forceinline__ float gelu_tanh(float y) { const float u = 0.7978845608028654f * (y + 0.044715f * y * y * y); return y * (1.0f - __builtin_amdgcn_rcpf(1.0f + __expf(2.0f * u))); }
;     __device__ __forceinline__ void operator()(const Acc& acc, const Unit& u, int wr, int wc, int fr, int fq) const {
;     ...
;             for (int m = 0; m < 4; ++m) { const int crow = u.pm * 256 + ai * 128 + wr * 64 + m * 16 + fr;
; #pragma unroll
;                 for (int bj = 0; bj < 2; ++bj)
; #pragma unroll
;                     for (int n = 0; n < 2; ++n) { const int col = bj * 128 + wc * 32 + n * 16 + fq * 4, t = col >> 4, cp = col & 15; const f32x4 v = acc[ai][bj][m][n];
;                         *(u32x2*)(Z + ((size_t)crow * 16 + t) * 256 + u.z * 16 + cp) = (u32x2){cvt_pk_bf16(gelu_tanh(v[0]), gelu_tanh(v[1])), cvt_pk_bf16(gelu_tanh(v[2]), gelu_tanh(v[3]))}; } }
.LBB0_1078:
	v_readlane_b32 s0, v253, 63
	v_readlane_b32 s1, v254, 0
	s_add_u32 s0, s0, 0x13200000
	s_addc_u32 s1, s1, 0
	s_lshl_b32 s2, s14, 8
	s_add_i32 s2, s2, s18
	v_add_u32_e32 v244, s2, v136
	v_ashrrev_i32_e32 v245, 4, v135
	v_lshl_add_u32 v246, v245, 2, s20
	v_ashrrev_i32_e32 v247, 4, v246
	v_lshlrev_b32_e32 v248, 13, v244
	v_lshl_add_u32 v248, v247, 9, v248
	v_lshl_add_u32 v248, v245, 3, v248
	s_lshl_b32 s74, s12, 5
	v_add_u32_e32 v248, s74, v248
	v_mov_b32_e32 v249, 0
	v_lshl_add_u64 v[250:251], s[0:1], 0, v[248:249]
	s_mov_b32 s66, 0x3d372713
	s_mov_b32 s67, 0x3d372713
	s_mov_b32 s68, 0x3f4c422a
	s_mov_b32 s69, 0x3f4c422a
	s_mov_b32 s70, 0x3fb8aa3b
	s_mov_b32 s71, 0x3fb8aa3b
	s_mov_b32 s98, 0x20000
	s_mov_b32 s99, 0x0
	s_mov_b32 s22, 0xa0000
	s_mov_b32 s23, 0x0
	s_mov_b32 s2, 0x1000
	s_mov_b32 s3, 0x0
	v_lshl_add_u64 v[246:247], v[250:251], 0, s[2:3]
	v_pk_mul_f32 v[240:241], v[124:125], s[66:67]
	v_pk_mul_f32 v[242:243], v[126:127], s[66:67]
	v_pk_mul_f32 v[240:241], v[124:125], v[240:241]
	v_pk_mul_f32 v[242:243], v[126:127], v[242:243]
	v_pk_fma_f32 v[240:241], v[124:125], v[240:241], v[124:125]
	v_pk_fma_f32 v[242:243], v[126:127], v[242:243], v[126:127]
	v_pk_mul_f32 v[240:241], v[240:241], s[68:69]
	v_pk_mul_f32 v[242:243], v[242:243], s[68:69]
	v_pk_add_f32 v[240:241], v[240:241], v[240:241]
	v_pk_add_f32 v[242:243], v[242:243], v[242:243]
	v_pk_mul_f32 v[240:241], v[240:241], s[70:71]
	v_pk_mul_f32 v[242:243], v[242:243], s[70:71]
	v_exp_f32_e32 v240, v240
	v_exp_f32_e32 v241, v241
	v_exp_f32_e32 v242, v242
	v_exp_f32_e32 v243, v243
	v_pk_add_f32 v[240:241], v[240:241], 1.0 op_sel_hi:[1,0]
	v_pk_add_f32 v[242:243], v[242:243], 1.0 op_sel_hi:[1,0]
	v_rcp_f32_e32 v240, v240
	v_rcp_f32_e32 v241, v241
	v_rcp_f32_e32 v242, v242
	v_rcp_f32_e32 v243, v243
	v_pk_add_f32 v[240:241], v[240:241], 1.0 op_sel_hi:[1,0] neg_lo:[1,0] neg_hi:[1,0]
	v_pk_add_f32 v[242:243], v[242:243], 1.0 op_sel_hi:[1,0] neg_lo:[1,0] neg_hi:[1,0]
	v_pk_mul_f32 v[124:125], v[124:125], v[240:241]
	v_pk_mul_f32 v[126:127], v[126:127], v[242:243]
	v_cvt_pk_bf16_f32 v124, v124, v125
	v_cvt_pk_bf16_f32 v125, v126, v127
	global_store_dwordx2 v[250:251], v[124:125], off sc0 sc1
	v_pk_mul_f32 v[240:241], v[120:121], s[66:67]
	v_pk_mul_f32 v[242:243], v[122:123], s[66:67]
	v_pk_mul_f32 v[240:241], v[120:121], v[240:241]
	v_pk_mul_f32 v[242:243], v[122:123], v[242:243]
	v_pk_fma_f32 v[240:241], v[120:121], v[240:241], v[120:121]
	v_pk_fma_f32 v[242:243], v[122:123], v[242:243], v[122:123]
	v_pk_mul_f32 v[240:241], v[240:241], s[68:69]
	v_pk_mul_f32 v[242:243], v[242:243], s[68:69]
	v_pk_add_f32 v[240:241], v[240:241], v[240:241]
	v_pk_add_f32 v[242:243], v[242:243], v[242:243]
	v_pk_mul_f32 v[240:241], v[240:241], s[70:71]
	v_pk_mul_f32 v[242:243], v[242:243], s[70:71]
	v_exp_f32_e32 v240, v240
	v_exp_f32_e32 v241, v241
	v_exp_f32_e32 v242, v242
	v_exp_f32_e32 v243, v243
	v_pk_add_f32 v[240:241], v[240:241], 1.0 op_sel_hi:[1,0]
	v_pk_add_f32 v[242:243], v[242:243], 1.0 op_sel_hi:[1,0]
	v_rcp_f32_e32 v240, v240
	v_rcp_f32_e32 v241, v241
	v_rcp_f32_e32 v242, v242
	v_rcp_f32_e32 v243, v243
	v_pk_add_f32 v[240:241], v[240:241], 1.0 op_sel_hi:[1,0] neg_lo:[1,0] neg_hi:[1,0]
	v_pk_add_f32 v[242:243], v[242:243], 1.0 op_sel_hi:[1,0] neg_lo:[1,0] neg_hi:[1,0]
	v_pk_mul_f32 v[120:121], v[120:121], v[240:241]
	v_pk_mul_f32 v[122:123], v[122:123], v[242:243]
	v_cvt_pk_bf16_f32 v120, v120, v121
	v_cvt_pk_bf16_f32 v121, v122, v123
	global_store_dwordx2 v[250:251], v[120:121], off offset:512 sc0 sc1
	v_pk_mul_f32 v[240:241], v[116:117], s[66:67]
	v_pk_mul_f32 v[242:243], v[118:119], s[66:67]
	v_pk_mul_f32 v[240:241], v[116:117], v[240:241]
	v_pk_mul_f32 v[242:243], v[118:119], v[242:243]
	v_pk_fma_f32 v[240:241], v[116:117], v[240:241], v[116:117]
	v_pk_fma_f32 v[242:243], v[118:119], v[242:243], v[118:119]
	v_pk_mul_f32 v[240:241], v[240:241], s[68:69]
	v_pk_mul_f32 v[242:243], v[242:243], s[68:69]
	v_pk_add_f32 v[240:241], v[240:241], v[240:241]
	v_pk_add_f32 v[242:243], v[242:243], v[242:243]
	v_pk_mul_f32 v[240:241], v[240:241], s[70:71]
	v_pk_mul_f32 v[242:243], v[242:243], s[70:71]
	v_exp_f32_e32 v240, v240
	v_exp_f32_e32 v241, v241
	v_exp_f32_e32 v242, v242
	v_exp_f32_e32 v243, v243
	v_pk_add_f32 v[240:241], v[240:241], 1.0 op_sel_hi:[1,0]
	v_pk_add_f32 v[242:243], v[242:243], 1.0 op_sel_hi:[1,0]
	v_rcp_f32_e32 v240, v240
	v_rcp_f32_e32 v241, v241
	v_rcp_f32_e32 v242, v242
	v_rcp_f32_e32 v243, v243
	v_pk_add_f32 v[240:241], v[240:241], 1.0 op_sel_hi:[1,0] neg_lo:[1,0] neg_hi:[1,0]
	v_pk_add_f32 v[242:243], v[242:243], 1.0 op_sel_hi:[1,0] neg_lo:[1,0] neg_hi:[1,0]
	v_pk_mul_f32 v[116:117], v[116:117], v[240:241]
	v_pk_mul_f32 v[118:119], v[118:119], v[242:243]
	v_cvt_pk_bf16_f32 v116, v116, v117
	v_cvt_pk_bf16_f32 v117, v118, v119
	global_store_dwordx2 v[246:247], v[116:117], off sc0 sc1
	v_pk_mul_f32 v[240:241], v[112:113], s[66:67]
	v_pk_mul_f32 v[242:243], v[114:115], s[66:67]
	v_pk_mul_f32 v[240:241], v[112:113], v[240:241]
	v_pk_mul_f32 v[242:243], v[114:115], v[242:243]
	v_pk_fma_f32 v[240:241], v[112:113], v[240:241], v[112:113]
	v_pk_fma_f32 v[242:243], v[114:115], v[242:243], v[114:115]
	v_pk_mul_f32 v[240:241], v[240:241], s[68:69]
	v_pk_mul_f32 v[242:243], v[242:243], s[68:69]
	v_pk_add_f32 v[240:241], v[240:241], v[240:241]
	v_pk_add_f32 v[242:243], v[242:243], v[242:243]
	v_pk_mul_f32 v[240:241], v[240:241], s[70:71]
	v_pk_mul_f32 v[242:243], v[242:243], s[70:71]
	v_exp_f32_e32 v240, v240
	v_exp_f32_e32 v241, v241
	v_exp_f32_e32 v242, v242
	v_exp_f32_e32 v243, v243
	v_pk_add_f32 v[240:241], v[240:241], 1.0 op_sel_hi:[1,0]
	v_pk_add_f32 v[242:243], v[242:243], 1.0 op_sel_hi:[1,0]
; __device__ __forceinline__ unsigned cvt_pk_bf16(float lo, float hi) { const f32x2_t v = {lo, hi}; const bf16x2_t b = __builtin_convertvector(v, bf16x2_t); return __builtin_bit_cast(unsigned, b); }
; __device__ __forceinline__ float gelu_tanh(float y) { const float u = 0.7978845608028654f * (y + 0.044715f * y * y * y); return y * (1.0f - __builtin_amdgcn_rcpf(1.0f + __expf(2.0f * u))); }
;     __device__ __forceinline__ void operator()(const Acc& acc, const Unit& u, int wr, int wc, int fr, int fq) const {
;     ...
;             for (int m = 0; m < 4; ++m) { const int crow = u.pm * 256 + ai * 128 + wr * 64 + m * 16 + fr;
; #pragma unroll
;                 for (int bj = 0; bj < 2; ++bj)
; #pragma unroll
;                     for (int n = 0; n < 2; ++n) { const int col = bj * 128 + wc * 32 + n * 16 + fq * 4, t = col >> 4, cp = col & 15; const f32x4 v = acc[ai][bj][m][n];
;                         *(u32x2*)(Z + ((size_t)crow * 16 + t) * 256 + u.z * 16 + cp) = (u32x2){cvt_pk_bf16(gelu_tanh(v[0]), gelu_tanh(v[1])), cvt_pk_bf16(gelu_tanh(v[2]), gelu_tanh(v[3]))}; } }
	v_rcp_f32_e32 v240, v240
	v_rcp_f32_e32 v241, v241
	v_rcp_f32_e32 v242, v242
	v_rcp_f32_e32 v243, v243
	v_pk_add_f32 v[240:241], v[240:241], 1.0 op_sel_hi:[1,0] neg_lo:[1,0] neg_hi:[1,0]
	v_pk_add_f32 v[242:243], v[242:243], 1.0 op_sel_hi:[1,0] neg_lo:[1,0] neg_hi:[1,0]
	v_pk_mul_f32 v[112:113], v[112:113], v[240:241]
	v_pk_mul_f32 v[114:115], v[114:115], v[242:243]
	v_cvt_pk_bf16_f32 v112, v112, v113
	v_cvt_pk_bf16_f32 v113, v114, v115
	global_store_dwordx2 v[246:247], v[112:113], off offset:512 sc0 sc1
	v_lshl_add_u64 v[250:251], v[250:251], 0, s[98:99]
	v_lshl_add_u64 v[246:247], v[246:247], 0, s[98:99]
	v_pk_mul_f32 v[240:241], v[108:109], s[66:67]
	v_pk_mul_f32 v[242:243], v[110:111], s[66:67]
	v_pk_mul_f32 v[240:241], v[108:109], v[240:241]
	v_pk_mul_f32 v[242:243], v[110:111], v[242:243]
	v_pk_fma_f32 v[240:241], v[108:109], v[240:241], v[108:109]
	v_pk_fma_f32 v[242:243], v[110:111], v[242:243], v[110:111]
	v_pk_mul_f32 v[240:241], v[240:241], s[68:69]
	v_pk_mul_f32 v[242:243], v[242:243], s[68:69]
	v_pk_add_f32 v[240:241], v[240:241], v[240:241]
	v_pk_add_f32 v[242:243], v[242:243], v[242:243]
	v_pk_mul_f32 v[240:241], v[240:241], s[70:71]
	v_pk_mul_f32 v[242:243], v[242:243], s[70:71]
	v_exp_f32_e32 v240, v240
	v_exp_f32_e32 v241, v241
	v_exp_f32_e32 v242, v242
	v_exp_f32_e32 v243, v243
	v_pk_add_f32 v[240:241], v[240:241], 1.0 op_sel_hi:[1,0]
	v_pk_add_f32 v[242:243], v[242:243], 1.0 op_sel_hi:[1,0]
	v_rcp_f32_e32 v240, v240
	v_rcp_f32_e32 v241, v241
	v_rcp_f32_e32 v242, v242
	v_rcp_f32_e32 v243, v243
	v_pk_add_f32 v[240:241], v[240:241], 1.0 op_sel_hi:[1,0] neg_lo:[1,0] neg_hi:[1,0]
	v_pk_add_f32 v[242:243], v[242:243], 1.0 op_sel_hi:[1,0] neg_lo:[1,0] neg_hi:[1,0]
	v_pk_mul_f32 v[108:109], v[108:109], v[240:241]
	v_pk_mul_f32 v[110:111], v[110:111], v[242:243]
	v_cvt_pk_bf16_f32 v108, v108, v109
	v_cvt_pk_bf16_f32 v109, v110, v111
	global_store_dwordx2 v[250:251], v[108:109], off sc0 sc1
	v_pk_mul_f32 v[240:241], v[104:105], s[66:67]
	v_pk_mul_f32 v[242:243], v[106:107], s[66:67]
	v_pk_mul_f32 v[240:241], v[104:105], v[240:241]
	v_pk_mul_f32 v[242:243], v[106:107], v[242:243]
	v_pk_fma_f32 v[240:241], v[104:105], v[240:241], v[104:105]
	v_pk_fma_f32 v[242:243], v[106:107], v[242:243], v[106:107]
	v_pk_mul_f32 v[240:241], v[240:241], s[68:69]
	v_pk_mul_f32 v[242:243], v[242:243], s[68:69]
	v_pk_add_f32 v[240:241], v[240:241], v[240:241]
	v_pk_add_f32 v[242:243], v[242:243], v[242:243]
	v_pk_mul_f32 v[240:241], v[240:241], s[70:71]
	v_pk_mul_f32 v[242:243], v[242:243], s[70:71]
	v_exp_f32_e32 v240, v240
	v_exp_f32_e32 v241, v241
	v_exp_f32_e32 v242, v242
	v_exp_f32_e32 v243, v243
	v_pk_add_f32 v[240:241], v[240:241], 1.0 op_sel_hi:[1,0]
	v_pk_add_f32 v[242:243], v[242:243], 1.0 op_sel_hi:[1,0]
	v_rcp_f32_e32 v240, v240
	v_rcp_f32_e32 v241, v241
	v_rcp_f32_e32 v242, v242
	v_rcp_f32_e32 v243, v243
	v_pk_add_f32 v[240:241], v[240:241], 1.0 op_sel_hi:[1,0] neg_lo:[1,0] neg_hi:[1,0]
	v_pk_add_f32 v[242:243], v[242:243], 1.0 op_sel_hi:[1,0] neg_lo:[1,0] neg_hi:[1,0]
	v_pk_mul_f32 v[104:105], v[104:105], v[240:241]
	v_pk_mul_f32 v[106:107], v[106:107], v[242:243]
	v_cvt_pk_bf16_f32 v104, v104, v105
	v_cvt_pk_bf16_f32 v105, v106, v107
	global_store_dwordx2 v[250:251], v[104:105], off offset:512 sc0 sc1
	v_pk_mul_f32 v[240:241], v[100:101], s[66:67]
	v_pk_mul_f32 v[242:243], v[102:103], s[66:67]
	v_pk_mul_f32 v[240:241], v[100:101], v[240:241]
	v_pk_mul_f32 v[242:243], v[102:103], v[242:243]
	v_pk_fma_f32 v[240:241], v[100:101], v[240:241], v[100:101]
	v_pk_fma_f32 v[242:243], v[102:103], v[242:243], v[102:103]
	v_pk_mul_f32 v[240:241], v[240:241], s[68:69]
	v_pk_mul_f32 v[242:243], v[242:243], s[68:69]
	v_pk_add_f32 v[240:241], v[240:241], v[240:241]
	v_pk_add_f32 v[242:243], v[242:243], v[242:243]
	v_pk_mul_f32 v[240:241], v[240:241], s[70:71]
	v_pk_mul_f32 v[242:243], v[242:243], s[70:71]
	v_exp_f32_e32 v240, v240
	v_exp_f32_e32 v241, v241
	v_exp_f32_e32 v242, v242
	v_exp_f32_e32 v243, v243
	v_pk_add_f32 v[240:241], v[240:241], 1.0 op_sel_hi:[1,0]
	v_pk_add_f32 v[242:243], v[242:243], 1.0 op_sel_hi:[1,0]
	v_rcp_f32_e32 v240, v240
	v_rcp_f32_e32 v241, v241
	v_rcp_f32_e32 v242, v242
	v_rcp_f32_e32 v243, v243
	v_pk_add_f32 v[240:241], v[240:241], 1.0 op_sel_hi:[1,0] neg_lo:[1,0] neg_hi:[1,0]
	v_pk_add_f32 v[242:243], v[242:243], 1.0 op_sel_hi:[1,0] neg_lo:[1,0] neg_hi:[1,0]
	v_pk_mul_f32 v[100:101], v[100:101], v[240:241]
	v_pk_mul_f32 v[102:103], v[102:103], v[242:243]
	v_cvt_pk_bf16_f32 v100, v100, v101
	v_cvt_pk_bf16_f32 v101, v102, v103
	global_store_dwordx2 v[246:247], v[100:101], off sc0 sc1
	v_pk_mul_f32 v[240:241], v[96:97], s[66:67]
	v_pk_mul_f32 v[242:243], v[98:99], s[66:67]
	v_pk_mul_f32 v[240:241], v[96:97], v[240:241]
	v_pk_mul_f32 v[242:243], v[98:99], v[242:243]
	v_pk_fma_f32 v[240:241], v[96:97], v[240:241], v[96:97]
	v_pk_fma_f32 v[242:243], v[98:99], v[242:243], v[98:99]
	v_pk_mul_f32 v[240:241], v[240:241], s[68:69]
	v_pk_mul_f32 v[242:243], v[242:243], s[68:69]
	v_pk_add_f32 v[240:241], v[240:241], v[240:241]
	v_pk_add_f32 v[242:243], v[242:243], v[242:243]
	v_pk_mul_f32 v[240:241], v[240:241], s[70:71]
	v_pk_mul_f32 v[242:243], v[242:243], s[70:71]
	v_exp_f32_e32 v240, v240
	v_exp_f32_e32 v241, v241
	v_exp_f32_e32 v242, v242
	v_exp_f32_e32 v243, v243
	v_pk_add_f32 v[240:241], v[240:241], 1.0 op_sel_hi:[1,0]
	v_pk_add_f32 v[242:243], v[242:243], 1.0 op_sel_hi:[1,0]
	v_rcp_f32_e32 v240, v240
	v_rcp_f32_e32 v241, v241
	v_rcp_f32_e32 v242, v242
	v_rcp_f32_e32 v243, v243
	v_pk_add_f32 v[240:241], v[240:241], 1.0 op_sel_hi:[1,0] neg_lo:[1,0] neg_hi:[1,0]
	v_pk_add_f32 v[242:243], v[242:243], 1.0 op_sel_hi:[1,0] neg_lo:[1,0] neg_hi:[1,0]
; __device__ __forceinline__ unsigned cvt_pk_bf16(float lo, float hi) { const f32x2_t v = {lo, hi}; const bf16x2_t b = __builtin_convertvector(v, bf16x2_t); return __builtin_bit_cast(unsigned, b); }
; __device__ __forceinline__ float gelu_tanh(float y) { const float u = 0.7978845608028654f * (y + 0.044715f * y * y * y); return y * (1.0f - __builtin_amdgcn_rcpf(1.0f + __expf(2.0f * u))); }
;     __device__ __forceinline__ void operator()(const Acc& acc, const Unit& u, int wr, int wc, int fr, int fq) const {
;     ...
;             for (int m = 0; m < 4; ++m) { const int crow = u.pm * 256 + ai * 128 + wr * 64 + m * 16 + fr;
; #pragma unroll
;                 for (int bj = 0; bj < 2; ++bj)
; #pragma unroll
;                     for (int n = 0; n < 2; ++n) { const int col = bj * 128 + wc * 32 + n * 16 + fq * 4, t = col >> 4, cp = col & 15; const f32x4 v = acc[ai][bj][m][n];
;                         *(u32x2*)(Z + ((size_t)crow * 16 + t) * 256 + u.z * 16 + cp) = (u32x2){cvt_pk_bf16(gelu_tanh(v[0]), gelu_tanh(v[1])), cvt_pk_bf16(gelu_tanh(v[2]), gelu_tanh(v[3]))}; } }
	v_pk_mul_f32 v[96:97], v[96:97], v[240:241]
	v_pk_mul_f32 v[98:99], v[98:99], v[242:243]
	v_cvt_pk_bf16_f32 v96, v96, v97
	v_cvt_pk_bf16_f32 v97, v98, v99
	global_store_dwordx2 v[246:247], v[96:97], off offset:512 sc0 sc1
	v_lshl_add_u64 v[250:251], v[250:251], 0, s[98:99]
	v_lshl_add_u64 v[246:247], v[246:247], 0, s[98:99]
	v_pk_mul_f32 v[240:241], v[92:93], s[66:67]
	v_pk_mul_f32 v[242:243], v[94:95], s[66:67]
	v_pk_mul_f32 v[240:241], v[92:93], v[240:241]
	v_pk_mul_f32 v[242:243], v[94:95], v[242:243]
	v_pk_fma_f32 v[240:241], v[92:93], v[240:241], v[92:93]
	v_pk_fma_f32 v[242:243], v[94:95], v[242:243], v[94:95]
	v_pk_mul_f32 v[240:241], v[240:241], s[68:69]
	v_pk_mul_f32 v[242:243], v[242:243], s[68:69]
	v_pk_add_f32 v[240:241], v[240:241], v[240:241]
	v_pk_add_f32 v[242:243], v[242:243], v[242:243]
	v_pk_mul_f32 v[240:241], v[240:241], s[70:71]
	v_pk_mul_f32 v[242:243], v[242:243], s[70:71]
	v_exp_f32_e32 v240, v240
	v_exp_f32_e32 v241, v241
	v_exp_f32_e32 v242, v242
	v_exp_f32_e32 v243, v243
	v_pk_add_f32 v[240:241], v[240:241], 1.0 op_sel_hi:[1,0]
	v_pk_add_f32 v[242:243], v[242:243], 1.0 op_sel_hi:[1,0]
	v_rcp_f32_e32 v240, v240
	v_rcp_f32_e32 v241, v241
	v_rcp_f32_e32 v242, v242
	v_rcp_f32_e32 v243, v243
	v_pk_add_f32 v[240:241], v[240:241], 1.0 op_sel_hi:[1,0] neg_lo:[1,0] neg_hi:[1,0]
	v_pk_add_f32 v[242:243], v[242:243], 1.0 op_sel_hi:[1,0] neg_lo:[1,0] neg_hi:[1,0]
	v_pk_mul_f32 v[92:93], v[92:93], v[240:241]
	v_pk_mul_f32 v[94:95], v[94:95], v[242:243]
	v_cvt_pk_bf16_f32 v92, v92, v93
	v_cvt_pk_bf16_f32 v93, v94, v95
	global_store_dwordx2 v[250:251], v[92:93], off sc0 sc1
	v_pk_mul_f32 v[240:241], v[88:89], s[66:67]
	v_pk_mul_f32 v[242:243], v[90:91], s[66:67]
	v_pk_mul_f32 v[240:241], v[88:89], v[240:241]
	v_pk_mul_f32 v[242:243], v[90:91], v[242:243]
	v_pk_fma_f32 v[240:241], v[88:89], v[240:241], v[88:89]
	v_pk_fma_f32 v[242:243], v[90:91], v[242:243], v[90:91]
	v_pk_mul_f32 v[240:241], v[240:241], s[68:69]
	v_pk_mul_f32 v[242:243], v[242:243], s[68:69]
	v_pk_add_f32 v[240:241], v[240:241], v[240:241]
	v_pk_add_f32 v[242:243], v[242:243], v[242:243]
	v_pk_mul_f32 v[240:241], v[240:241], s[70:71]
	v_pk_mul_f32 v[242:243], v[242:243], s[70:71]
	v_exp_f32_e32 v240, v240
	v_exp_f32_e32 v241, v241
	v_exp_f32_e32 v242, v242
	v_exp_f32_e32 v243, v243
	v_pk_add_f32 v[240:241], v[240:241], 1.0 op_sel_hi:[1,0]
	v_pk_add_f32 v[242:243], v[242:243], 1.0 op_sel_hi:[1,0]
	v_rcp_f32_e32 v240, v240
	v_rcp_f32_e32 v241, v241
	v_rcp_f32_e32 v242, v242
	v_rcp_f32_e32 v243, v243
	v_pk_add_f32 v[240:241], v[240:241], 1.0 op_sel_hi:[1,0] neg_lo:[1,0] neg_hi:[1,0]
	v_pk_add_f32 v[242:243], v[242:243], 1.0 op_sel_hi:[1,0] neg_lo:[1,0] neg_hi:[1,0]
	v_pk_mul_f32 v[88:89], v[88:89], v[240:241]
	v_pk_mul_f32 v[90:91], v[90:91], v[242:243]
	v_cvt_pk_bf16_f32 v88, v88, v89
	v_cvt_pk_bf16_f32 v89, v90, v91
	global_store_dwordx2 v[250:251], v[88:89], off offset:512 sc0 sc1
	v_pk_mul_f32 v[240:241], v[84:85], s[66:67]
	v_pk_mul_f32 v[242:243], v[86:87], s[66:67]
	v_pk_mul_f32 v[240:241], v[84:85], v[240:241]
	v_pk_mul_f32 v[242:243], v[86:87], v[242:243]
	v_pk_fma_f32 v[240:241], v[84:85], v[240:241], v[84:85]
	v_pk_fma_f32 v[242:243], v[86:87], v[242:243], v[86:87]
	v_pk_mul_f32 v[240:241], v[240:241], s[68:69]
	v_pk_mul_f32 v[242:243], v[242:243], s[68:69]
	v_pk_add_f32 v[240:241], v[240:241], v[240:241]
	v_pk_add_f32 v[242:243], v[242:243], v[242:243]
	v_pk_mul_f32 v[240:241], v[240:241], s[70:71]
	v_pk_mul_f32 v[242:243], v[242:243], s[70:71]
	v_exp_f32_e32 v240, v240
	v_exp_f32_e32 v241, v241
	v_exp_f32_e32 v242, v242
	v_exp_f32_e32 v243, v243
	v_pk_add_f32 v[240:241], v[240:241], 1.0 op_sel_hi:[1,0]
	v_pk_add_f32 v[242:243], v[242:243], 1.0 op_sel_hi:[1,0]
	v_rcp_f32_e32 v240, v240
	v_rcp_f32_e32 v241, v241
	v_rcp_f32_e32 v242, v242
	v_rcp_f32_e32 v243, v243
	v_pk_add_f32 v[240:241], v[240:241], 1.0 op_sel_hi:[1,0] neg_lo:[1,0] neg_hi:[1,0]
	v_pk_add_f32 v[242:243], v[242:243], 1.0 op_sel_hi:[1,0] neg_lo:[1,0] neg_hi:[1,0]
	v_pk_mul_f32 v[84:85], v[84:85], v[240:241]
	v_pk_mul_f32 v[86:87], v[86:87], v[242:243]
	v_cvt_pk_bf16_f32 v84, v84, v85
	v_cvt_pk_bf16_f32 v85, v86, v87
	global_store_dwordx2 v[246:247], v[84:85], off sc0 sc1
	v_pk_mul_f32 v[240:241], v[80:81], s[66:67]
	v_pk_mul_f32 v[242:243], v[82:83], s[66:67]
	v_pk_mul_f32 v[240:241], v[80:81], v[240:241]
	v_pk_mul_f32 v[242:243], v[82:83], v[242:243]
	v_pk_fma_f32 v[240:241], v[80:81], v[240:241], v[80:81]
	v_pk_fma_f32 v[242:243], v[82:83], v[242:243], v[82:83]
	v_pk_mul_f32 v[240:241], v[240:241], s[68:69]
	v_pk_mul_f32 v[242:243], v[242:243], s[68:69]
	v_pk_add_f32 v[240:241], v[240:241], v[240:241]
	v_pk_add_f32 v[242:243], v[242:243], v[242:243]
	v_pk_mul_f32 v[240:241], v[240:241], s[70:71]
	v_pk_mul_f32 v[242:243], v[242:243], s[70:71]
	v_exp_f32_e32 v240, v240
	v_exp_f32_e32 v241, v241
	v_exp_f32_e32 v242, v242
	v_exp_f32_e32 v243, v243
	v_pk_add_f32 v[240:241], v[240:241], 1.0 op_sel_hi:[1,0]
	v_pk_add_f32 v[242:243], v[242:243], 1.0 op_sel_hi:[1,0]
	v_rcp_f32_e32 v240, v240
	v_rcp_f32_e32 v241, v241
	v_rcp_f32_e32 v242, v242
	v_rcp_f32_e32 v243, v243
	v_pk_add_f32 v[240:241], v[240:241], 1.0 op_sel_hi:[1,0] neg_lo:[1,0] neg_hi:[1,0]
	v_pk_add_f32 v[242:243], v[242:243], 1.0 op_sel_hi:[1,0] neg_lo:[1,0] neg_hi:[1,0]
	v_pk_mul_f32 v[80:81], v[80:81], v[240:241]
	v_pk_mul_f32 v[82:83], v[82:83], v[242:243]
	v_cvt_pk_bf16_f32 v80, v80, v81
	v_cvt_pk_bf16_f32 v81, v82, v83
	global_store_dwordx2 v[246:247], v[80:81], off offset:512 sc0 sc1
	v_lshl_add_u64 v[250:251], v[250:251], 0, s[98:99]
	v_lshl_add_u64 v[246:247], v[246:247], 0, s[98:99]
	v_pk_mul_f32 v[240:241], v[76:77], s[66:67]
; __device__ __forceinline__ unsigned cvt_pk_bf16(float lo, float hi) { const f32x2_t v = {lo, hi}; const bf16x2_t b = __builtin_convertvector(v, bf16x2_t); return __builtin_bit_cast(unsigned, b); }
; __device__ __forceinline__ float gelu_tanh(float y) { const float u = 0.7978845608028654f * (y + 0.044715f * y * y * y); return y * (1.0f - __builtin_amdgcn_rcpf(1.0f + __expf(2.0f * u))); }
;     __device__ __forceinline__ void operator()(const Acc& acc, const Unit& u, int wr, int wc, int fr, int fq) const {
;     ...
;             for (int m = 0; m < 4; ++m) { const int crow = u.pm * 256 + ai * 128 + wr * 64 + m * 16 + fr;
; #pragma unroll
;                 for (int bj = 0; bj < 2; ++bj)
; #pragma unroll
;                     for (int n = 0; n < 2; ++n) { const int col = bj * 128 + wc * 32 + n * 16 + fq * 4, t = col >> 4, cp = col & 15; const f32x4 v = acc[ai][bj][m][n];
;                         *(u32x2*)(Z + ((size_t)crow * 16 + t) * 256 + u.z * 16 + cp) = (u32x2){cvt_pk_bf16(gelu_tanh(v[0]), gelu_tanh(v[1])), cvt_pk_bf16(gelu_tanh(v[2]), gelu_tanh(v[3]))}; } }
	v_pk_mul_f32 v[242:243], v[78:79], s[66:67]
	v_pk_mul_f32 v[240:241], v[76:77], v[240:241]
	v_pk_mul_f32 v[242:243], v[78:79], v[242:243]
	v_pk_fma_f32 v[240:241], v[76:77], v[240:241], v[76:77]
	v_pk_fma_f32 v[242:243], v[78:79], v[242:243], v[78:79]
	v_pk_mul_f32 v[240:241], v[240:241], s[68:69]
	v_pk_mul_f32 v[242:243], v[242:243], s[68:69]
	v_pk_add_f32 v[240:241], v[240:241], v[240:241]
	v_pk_add_f32 v[242:243], v[242:243], v[242:243]
	v_pk_mul_f32 v[240:241], v[240:241], s[70:71]
	v_pk_mul_f32 v[242:243], v[242:243], s[70:71]
	v_exp_f32_e32 v240, v240
	v_exp_f32_e32 v241, v241
	v_exp_f32_e32 v242, v242
	v_exp_f32_e32 v243, v243
	v_pk_add_f32 v[240:241], v[240:241], 1.0 op_sel_hi:[1,0]
	v_pk_add_f32 v[242:243], v[242:243], 1.0 op_sel_hi:[1,0]
	v_rcp_f32_e32 v240, v240
	v_rcp_f32_e32 v241, v241
	v_rcp_f32_e32 v242, v242
	v_rcp_f32_e32 v243, v243
	v_pk_add_f32 v[240:241], v[240:241], 1.0 op_sel_hi:[1,0] neg_lo:[1,0] neg_hi:[1,0]
	v_pk_add_f32 v[242:243], v[242:243], 1.0 op_sel_hi:[1,0] neg_lo:[1,0] neg_hi:[1,0]
	v_pk_mul_f32 v[76:77], v[76:77], v[240:241]
	v_pk_mul_f32 v[78:79], v[78:79], v[242:243]
	v_cvt_pk_bf16_f32 v76, v76, v77
	v_cvt_pk_bf16_f32 v77, v78, v79
	global_store_dwordx2 v[250:251], v[76:77], off sc0 sc1
	v_pk_mul_f32 v[240:241], v[72:73], s[66:67]
	v_pk_mul_f32 v[242:243], v[74:75], s[66:67]
	v_pk_mul_f32 v[240:241], v[72:73], v[240:241]
	v_pk_mul_f32 v[242:243], v[74:75], v[242:243]
	v_pk_fma_f32 v[240:241], v[72:73], v[240:241], v[72:73]
	v_pk_fma_f32 v[242:243], v[74:75], v[242:243], v[74:75]
	v_pk_mul_f32 v[240:241], v[240:241], s[68:69]
	v_pk_mul_f32 v[242:243], v[242:243], s[68:69]
	v_pk_add_f32 v[240:241], v[240:241], v[240:241]
	v_pk_add_f32 v[242:243], v[242:243], v[242:243]
	v_pk_mul_f32 v[240:241], v[240:241], s[70:71]
	v_pk_mul_f32 v[242:243], v[242:243], s[70:71]
	v_exp_f32_e32 v240, v240
	v_exp_f32_e32 v241, v241
	v_exp_f32_e32 v242, v242
	v_exp_f32_e32 v243, v243
	v_pk_add_f32 v[240:241], v[240:241], 1.0 op_sel_hi:[1,0]
	v_pk_add_f32 v[242:243], v[242:243], 1.0 op_sel_hi:[1,0]
	v_rcp_f32_e32 v240, v240
	v_rcp_f32_e32 v241, v241
	v_rcp_f32_e32 v242, v242
	v_rcp_f32_e32 v243, v243
	v_pk_add_f32 v[240:241], v[240:241], 1.0 op_sel_hi:[1,0] neg_lo:[1,0] neg_hi:[1,0]
	v_pk_add_f32 v[242:243], v[242:243], 1.0 op_sel_hi:[1,0] neg_lo:[1,0] neg_hi:[1,0]
	v_pk_mul_f32 v[72:73], v[72:73], v[240:241]
	v_pk_mul_f32 v[74:75], v[74:75], v[242:243]
	v_cvt_pk_bf16_f32 v72, v72, v73
	v_cvt_pk_bf16_f32 v73, v74, v75
	global_store_dwordx2 v[250:251], v[72:73], off offset:512 sc0 sc1
	v_pk_mul_f32 v[240:241], v[68:69], s[66:67]
	v_pk_mul_f32 v[242:243], v[70:71], s[66:67]
	v_pk_mul_f32 v[240:241], v[68:69], v[240:241]
	v_pk_mul_f32 v[242:243], v[70:71], v[242:243]
	v_pk_fma_f32 v[240:241], v[68:69], v[240:241], v[68:69]
	v_pk_fma_f32 v[242:243], v[70:71], v[242:243], v[70:71]
	v_pk_mul_f32 v[240:241], v[240:241], s[68:69]
	v_pk_mul_f32 v[242:243], v[242:243], s[68:69]
	v_pk_add_f32 v[240:241], v[240:241], v[240:241]
	v_pk_add_f32 v[242:243], v[242:243], v[242:243]
	v_pk_mul_f32 v[240:241], v[240:241], s[70:71]
	v_pk_mul_f32 v[242:243], v[242:243], s[70:71]
	v_exp_f32_e32 v240, v240
	v_exp_f32_e32 v241, v241
	v_exp_f32_e32 v242, v242
	v_exp_f32_e32 v243, v243
	v_pk_add_f32 v[240:241], v[240:241], 1.0 op_sel_hi:[1,0]
	v_pk_add_f32 v[242:243], v[242:243], 1.0 op_sel_hi:[1,0]
	v_rcp_f32_e32 v240, v240
	v_rcp_f32_e32 v241, v241
	v_rcp_f32_e32 v242, v242
	v_rcp_f32_e32 v243, v243
	v_pk_add_f32 v[240:241], v[240:241], 1.0 op_sel_hi:[1,0] neg_lo:[1,0] neg_hi:[1,0]
	v_pk_add_f32 v[242:243], v[242:243], 1.0 op_sel_hi:[1,0] neg_lo:[1,0] neg_hi:[1,0]
	v_pk_mul_f32 v[68:69], v[68:69], v[240:241]
	v_pk_mul_f32 v[70:71], v[70:71], v[242:243]
	v_cvt_pk_bf16_f32 v68, v68, v69
	v_cvt_pk_bf16_f32 v69, v70, v71
	global_store_dwordx2 v[246:247], v[68:69], off sc0 sc1
	v_pk_mul_f32 v[240:241], v[64:65], s[66:67]
	v_pk_mul_f32 v[242:243], v[66:67], s[66:67]
	v_pk_mul_f32 v[240:241], v[64:65], v[240:241]
	v_pk_mul_f32 v[242:243], v[66:67], v[242:243]
	v_pk_fma_f32 v[240:241], v[64:65], v[240:241], v[64:65]
	v_pk_fma_f32 v[242:243], v[66:67], v[242:243], v[66:67]
	v_pk_mul_f32 v[240:241], v[240:241], s[68:69]
	v_pk_mul_f32 v[242:243], v[242:243], s[68:69]
	v_pk_add_f32 v[240:241], v[240:241], v[240:241]
	v_pk_add_f32 v[242:243], v[242:243], v[242:243]
	v_pk_mul_f32 v[240:241], v[240:241], s[70:71]
	v_pk_mul_f32 v[242:243], v[242:243], s[70:71]
	v_exp_f32_e32 v240, v240
	v_exp_f32_e32 v241, v241
	v_exp_f32_e32 v242, v242
	v_exp_f32_e32 v243, v243
	v_pk_add_f32 v[240:241], v[240:241], 1.0 op_sel_hi:[1,0]
	v_pk_add_f32 v[242:243], v[242:243], 1.0 op_sel_hi:[1,0]
	v_rcp_f32_e32 v240, v240
	v_rcp_f32_e32 v241, v241
	v_rcp_f32_e32 v242, v242
	v_rcp_f32_e32 v243, v243
	v_pk_add_f32 v[240:241], v[240:241], 1.0 op_sel_hi:[1,0] neg_lo:[1,0] neg_hi:[1,0]
	v_pk_add_f32 v[242:243], v[242:243], 1.0 op_sel_hi:[1,0] neg_lo:[1,0] neg_hi:[1,0]
	v_pk_mul_f32 v[64:65], v[64:65], v[240:241]
	v_pk_mul_f32 v[66:67], v[66:67], v[242:243]
	v_cvt_pk_bf16_f32 v64, v64, v65
	v_cvt_pk_bf16_f32 v65, v66, v67
	global_store_dwordx2 v[246:247], v[64:65], off offset:512 sc0 sc1
	v_lshl_add_u64 v[250:251], v[250:251], 0, s[22:23]
	v_lshl_add_u64 v[246:247], v[246:247], 0, s[22:23]
	v_pk_mul_f32 v[240:241], v[60:61], s[66:67]
	v_pk_mul_f32 v[242:243], v[62:63], s[66:67]
	v_pk_mul_f32 v[240:241], v[60:61], v[240:241]
	v_pk_mul_f32 v[242:243], v[62:63], v[242:243]
	v_pk_fma_f32 v[240:241], v[60:61], v[240:241], v[60:61]
	v_pk_fma_f32 v[242:243], v[62:63], v[242:243], v[62:63]
	v_pk_mul_f32 v[240:241], v[240:241], s[68:69]
	v_pk_mul_f32 v[242:243], v[242:243], s[68:69]
; __device__ __forceinline__ unsigned cvt_pk_bf16(float lo, float hi) { const f32x2_t v = {lo, hi}; const bf16x2_t b = __builtin_convertvector(v, bf16x2_t); return __builtin_bit_cast(unsigned, b); }
; __device__ __forceinline__ float gelu_tanh(float y) { const float u = 0.7978845608028654f * (y + 0.044715f * y * y * y); return y * (1.0f - __builtin_amdgcn_rcpf(1.0f + __expf(2.0f * u))); }
;     __device__ __forceinline__ void operator()(const Acc& acc, const Unit& u, int wr, int wc, int fr, int fq) const {
;     ...
;             for (int m = 0; m < 4; ++m) { const int crow = u.pm * 256 + ai * 128 + wr * 64 + m * 16 + fr;
; #pragma unroll
;                 for (int bj = 0; bj < 2; ++bj)
; #pragma unroll
;                     for (int n = 0; n < 2; ++n) { const int col = bj * 128 + wc * 32 + n * 16 + fq * 4, t = col >> 4, cp = col & 15; const f32x4 v = acc[ai][bj][m][n];
;                         *(u32x2*)(Z + ((size_t)crow * 16 + t) * 256 + u.z * 16 + cp) = (u32x2){cvt_pk_bf16(gelu_tanh(v[0]), gelu_tanh(v[1])), cvt_pk_bf16(gelu_tanh(v[2]), gelu_tanh(v[3]))}; } }
	v_pk_add_f32 v[240:241], v[240:241], v[240:241]
	v_pk_add_f32 v[242:243], v[242:243], v[242:243]
	v_pk_mul_f32 v[240:241], v[240:241], s[70:71]
	v_pk_mul_f32 v[242:243], v[242:243], s[70:71]
	v_exp_f32_e32 v240, v240
	v_exp_f32_e32 v241, v241
	v_exp_f32_e32 v242, v242
	v_exp_f32_e32 v243, v243
	v_pk_add_f32 v[240:241], v[240:241], 1.0 op_sel_hi:[1,0]
	v_pk_add_f32 v[242:243], v[242:243], 1.0 op_sel_hi:[1,0]
	v_rcp_f32_e32 v240, v240
	v_rcp_f32_e32 v241, v241
	v_rcp_f32_e32 v242, v242
	v_rcp_f32_e32 v243, v243
	v_pk_add_f32 v[240:241], v[240:241], 1.0 op_sel_hi:[1,0] neg_lo:[1,0] neg_hi:[1,0]
	v_pk_add_f32 v[242:243], v[242:243], 1.0 op_sel_hi:[1,0] neg_lo:[1,0] neg_hi:[1,0]
	v_pk_mul_f32 v[60:61], v[60:61], v[240:241]
	v_pk_mul_f32 v[62:63], v[62:63], v[242:243]
	v_cvt_pk_bf16_f32 v60, v60, v61
	v_cvt_pk_bf16_f32 v61, v62, v63
	global_store_dwordx2 v[250:251], v[60:61], off sc0 sc1
	v_pk_mul_f32 v[240:241], v[56:57], s[66:67]
	v_pk_mul_f32 v[242:243], v[58:59], s[66:67]
	v_pk_mul_f32 v[240:241], v[56:57], v[240:241]
	v_pk_mul_f32 v[242:243], v[58:59], v[242:243]
	v_pk_fma_f32 v[240:241], v[56:57], v[240:241], v[56:57]
	v_pk_fma_f32 v[242:243], v[58:59], v[242:243], v[58:59]
	v_pk_mul_f32 v[240:241], v[240:241], s[68:69]
	v_pk_mul_f32 v[242:243], v[242:243], s[68:69]
	v_pk_add_f32 v[240:241], v[240:241], v[240:241]
	v_pk_add_f32 v[242:243], v[242:243], v[242:243]
	v_pk_mul_f32 v[240:241], v[240:241], s[70:71]
	v_pk_mul_f32 v[242:243], v[242:243], s[70:71]
	v_exp_f32_e32 v240, v240
	v_exp_f32_e32 v241, v241
	v_exp_f32_e32 v242, v242
	v_exp_f32_e32 v243, v243
	v_pk_add_f32 v[240:241], v[240:241], 1.0 op_sel_hi:[1,0]
	v_pk_add_f32 v[242:243], v[242:243], 1.0 op_sel_hi:[1,0]
	v_rcp_f32_e32 v240, v240
	v_rcp_f32_e32 v241, v241
	v_rcp_f32_e32 v242, v242
	v_rcp_f32_e32 v243, v243
	v_pk_add_f32 v[240:241], v[240:241], 1.0 op_sel_hi:[1,0] neg_lo:[1,0] neg_hi:[1,0]
	v_pk_add_f32 v[242:243], v[242:243], 1.0 op_sel_hi:[1,0] neg_lo:[1,0] neg_hi:[1,0]
	v_pk_mul_f32 v[56:57], v[56:57], v[240:241]
	v_pk_mul_f32 v[58:59], v[58:59], v[242:243]
	v_cvt_pk_bf16_f32 v56, v56, v57
	v_cvt_pk_bf16_f32 v57, v58, v59
	global_store_dwordx2 v[250:251], v[56:57], off offset:512 sc0 sc1
	v_pk_mul_f32 v[240:241], v[52:53], s[66:67]
	v_pk_mul_f32 v[242:243], v[54:55], s[66:67]
	v_pk_mul_f32 v[240:241], v[52:53], v[240:241]
	v_pk_mul_f32 v[242:243], v[54:55], v[242:243]
	v_pk_fma_f32 v[240:241], v[52:53], v[240:241], v[52:53]
	v_pk_fma_f32 v[242:243], v[54:55], v[242:243], v[54:55]
	v_pk_mul_f32 v[240:241], v[240:241], s[68:69]
	v_pk_mul_f32 v[242:243], v[242:243], s[68:69]
	v_pk_add_f32 v[240:241], v[240:241], v[240:241]
	v_pk_add_f32 v[242:243], v[242:243], v[242:243]
	v_pk_mul_f32 v[240:241], v[240:241], s[70:71]
	v_pk_mul_f32 v[242:243], v[242:243], s[70:71]
	v_exp_f32_e32 v240, v240
	v_exp_f32_e32 v241, v241
	v_exp_f32_e32 v242, v242
	v_exp_f32_e32 v243, v243
	v_pk_add_f32 v[240:241], v[240:241], 1.0 op_sel_hi:[1,0]
	v_pk_add_f32 v[242:243], v[242:243], 1.0 op_sel_hi:[1,0]
	v_rcp_f32_e32 v240, v240
	v_rcp_f32_e32 v241, v241
	v_rcp_f32_e32 v242, v242
	v_rcp_f32_e32 v243, v243
	v_pk_add_f32 v[240:241], v[240:241], 1.0 op_sel_hi:[1,0] neg_lo:[1,0] neg_hi:[1,0]
	v_pk_add_f32 v[242:243], v[242:243], 1.0 op_sel_hi:[1,0] neg_lo:[1,0] neg_hi:[1,0]
	v_pk_mul_f32 v[52:53], v[52:53], v[240:241]
	v_pk_mul_f32 v[54:55], v[54:55], v[242:243]
	v_cvt_pk_bf16_f32 v52, v52, v53
	v_cvt_pk_bf16_f32 v53, v54, v55
	global_store_dwordx2 v[246:247], v[52:53], off sc0 sc1
	v_pk_mul_f32 v[240:241], v[48:49], s[66:67]
	v_pk_mul_f32 v[242:243], v[50:51], s[66:67]
	v_pk_mul_f32 v[240:241], v[48:49], v[240:241]
	v_pk_mul_f32 v[242:243], v[50:51], v[242:243]
	v_pk_fma_f32 v[240:241], v[48:49], v[240:241], v[48:49]
	v_pk_fma_f32 v[242:243], v[50:51], v[242:243], v[50:51]
	v_pk_mul_f32 v[240:241], v[240:241], s[68:69]
	v_pk_mul_f32 v[242:243], v[242:243], s[68:69]
	v_pk_add_f32 v[240:241], v[240:241], v[240:241]
	v_pk_add_f32 v[242:243], v[242:243], v[242:243]
	v_pk_mul_f32 v[240:241], v[240:241], s[70:71]
	v_pk_mul_f32 v[242:243], v[242:243], s[70:71]
	v_exp_f32_e32 v240, v240
	v_exp_f32_e32 v241, v241
	v_exp_f32_e32 v242, v242
	v_exp_f32_e32 v243, v243
	v_pk_add_f32 v[240:241], v[240:241], 1.0 op_sel_hi:[1,0]
	v_pk_add_f32 v[242:243], v[242:243], 1.0 op_sel_hi:[1,0]
	v_rcp_f32_e32 v240, v240
	v_rcp_f32_e32 v241, v241
	v_rcp_f32_e32 v242, v242
	v_rcp_f32_e32 v243, v243
	v_pk_add_f32 v[240:241], v[240:241], 1.0 op_sel_hi:[1,0] neg_lo:[1,0] neg_hi:[1,0]
	v_pk_add_f32 v[242:243], v[242:243], 1.0 op_sel_hi:[1,0] neg_lo:[1,0] neg_hi:[1,0]
	v_pk_mul_f32 v[48:49], v[48:49], v[240:241]
	v_pk_mul_f32 v[50:51], v[50:51], v[242:243]
	v_cvt_pk_bf16_f32 v48, v48, v49
	v_cvt_pk_bf16_f32 v49, v50, v51
	global_store_dwordx2 v[246:247], v[48:49], off offset:512 sc0 sc1
	v_lshl_add_u64 v[250:251], v[250:251], 0, s[98:99]
	v_lshl_add_u64 v[246:247], v[246:247], 0, s[98:99]
	v_pk_mul_f32 v[240:241], v[44:45], s[66:67]
	v_pk_mul_f32 v[242:243], v[46:47], s[66:67]
	v_pk_mul_f32 v[240:241], v[44:45], v[240:241]
	v_pk_mul_f32 v[242:243], v[46:47], v[242:243]
	v_pk_fma_f32 v[240:241], v[44:45], v[240:241], v[44:45]
	v_pk_fma_f32 v[242:243], v[46:47], v[242:243], v[46:47]
	v_pk_mul_f32 v[240:241], v[240:241], s[68:69]
	v_pk_mul_f32 v[242:243], v[242:243], s[68:69]
	v_pk_add_f32 v[240:241], v[240:241], v[240:241]
	v_pk_add_f32 v[242:243], v[242:243], v[242:243]
	v_pk_mul_f32 v[240:241], v[240:241], s[70:71]
	v_pk_mul_f32 v[242:243], v[242:243], s[70:71]
	v_exp_f32_e32 v240, v240
	v_exp_f32_e32 v241, v241
	v_exp_f32_e32 v242, v242
	v_exp_f32_e32 v243, v243
	v_pk_add_f32 v[240:241], v[240:241], 1.0 op_sel_hi:[1,0]
; __device__ __forceinline__ unsigned cvt_pk_bf16(float lo, float hi) { const f32x2_t v = {lo, hi}; const bf16x2_t b = __builtin_convertvector(v, bf16x2_t); return __builtin_bit_cast(unsigned, b); }
; __device__ __forceinline__ float gelu_tanh(float y) { const float u = 0.7978845608028654f * (y + 0.044715f * y * y * y); return y * (1.0f - __builtin_amdgcn_rcpf(1.0f + __expf(2.0f * u))); }
;     __device__ __forceinline__ void operator()(const Acc& acc, const Unit& u, int wr, int wc, int fr, int fq) const {
;     ...
;             for (int m = 0; m < 4; ++m) { const int crow = u.pm * 256 + ai * 128 + wr * 64 + m * 16 + fr;
; #pragma unroll
;                 for (int bj = 0; bj < 2; ++bj)
; #pragma unroll
;                     for (int n = 0; n < 2; ++n) { const int col = bj * 128 + wc * 32 + n * 16 + fq * 4, t = col >> 4, cp = col & 15; const f32x4 v = acc[ai][bj][m][n];
;                         *(u32x2*)(Z + ((size_t)crow * 16 + t) * 256 + u.z * 16 + cp) = (u32x2){cvt_pk_bf16(gelu_tanh(v[0]), gelu_tanh(v[1])), cvt_pk_bf16(gelu_tanh(v[2]), gelu_tanh(v[3]))}; } }
	v_pk_add_f32 v[242:243], v[242:243], 1.0 op_sel_hi:[1,0]
	v_rcp_f32_e32 v240, v240
	v_rcp_f32_e32 v241, v241
	v_rcp_f32_e32 v242, v242
	v_rcp_f32_e32 v243, v243
	v_pk_add_f32 v[240:241], v[240:241], 1.0 op_sel_hi:[1,0] neg_lo:[1,0] neg_hi:[1,0]
	v_pk_add_f32 v[242:243], v[242:243], 1.0 op_sel_hi:[1,0] neg_lo:[1,0] neg_hi:[1,0]
	v_pk_mul_f32 v[44:45], v[44:45], v[240:241]
	v_pk_mul_f32 v[46:47], v[46:47], v[242:243]
	v_cvt_pk_bf16_f32 v44, v44, v45
	v_cvt_pk_bf16_f32 v45, v46, v47
	global_store_dwordx2 v[250:251], v[44:45], off sc0 sc1
	v_pk_mul_f32 v[240:241], v[40:41], s[66:67]
	v_pk_mul_f32 v[242:243], v[42:43], s[66:67]
	v_pk_mul_f32 v[240:241], v[40:41], v[240:241]
	v_pk_mul_f32 v[242:243], v[42:43], v[242:243]
	v_pk_fma_f32 v[240:241], v[40:41], v[240:241], v[40:41]
	v_pk_fma_f32 v[242:243], v[42:43], v[242:243], v[42:43]
	v_pk_mul_f32 v[240:241], v[240:241], s[68:69]
	v_pk_mul_f32 v[242:243], v[242:243], s[68:69]
	v_pk_add_f32 v[240:241], v[240:241], v[240:241]
	v_pk_add_f32 v[242:243], v[242:243], v[242:243]
	v_pk_mul_f32 v[240:241], v[240:241], s[70:71]
	v_pk_mul_f32 v[242:243], v[242:243], s[70:71]
	v_exp_f32_e32 v240, v240
	v_exp_f32_e32 v241, v241
	v_exp_f32_e32 v242, v242
	v_exp_f32_e32 v243, v243
	v_pk_add_f32 v[240:241], v[240:241], 1.0 op_sel_hi:[1,0]
	v_pk_add_f32 v[242:243], v[242:243], 1.0 op_sel_hi:[1,0]
	v_rcp_f32_e32 v240, v240
	v_rcp_f32_e32 v241, v241
	v_rcp_f32_e32 v242, v242
	v_rcp_f32_e32 v243, v243
	v_pk_add_f32 v[240:241], v[240:241], 1.0 op_sel_hi:[1,0] neg_lo:[1,0] neg_hi:[1,0]
	v_pk_add_f32 v[242:243], v[242:243], 1.0 op_sel_hi:[1,0] neg_lo:[1,0] neg_hi:[1,0]
	v_pk_mul_f32 v[40:41], v[40:41], v[240:241]
	v_pk_mul_f32 v[42:43], v[42:43], v[242:243]
	v_cvt_pk_bf16_f32 v40, v40, v41
	v_cvt_pk_bf16_f32 v41, v42, v43
	global_store_dwordx2 v[250:251], v[40:41], off offset:512 sc0 sc1
	v_pk_mul_f32 v[240:241], v[36:37], s[66:67]
	v_pk_mul_f32 v[242:243], v[38:39], s[66:67]
	v_pk_mul_f32 v[240:241], v[36:37], v[240:241]
	v_pk_mul_f32 v[242:243], v[38:39], v[242:243]
	v_pk_fma_f32 v[240:241], v[36:37], v[240:241], v[36:37]
	v_pk_fma_f32 v[242:243], v[38:39], v[242:243], v[38:39]
	v_pk_mul_f32 v[240:241], v[240:241], s[68:69]
	v_pk_mul_f32 v[242:243], v[242:243], s[68:69]
	v_pk_add_f32 v[240:241], v[240:241], v[240:241]
	v_pk_add_f32 v[242:243], v[242:243], v[242:243]
	v_pk_mul_f32 v[240:241], v[240:241], s[70:71]
	v_pk_mul_f32 v[242:243], v[242:243], s[70:71]
	v_exp_f32_e32 v240, v240
	v_exp_f32_e32 v241, v241
	v_exp_f32_e32 v242, v242
	v_exp_f32_e32 v243, v243
	v_pk_add_f32 v[240:241], v[240:241], 1.0 op_sel_hi:[1,0]
	v_pk_add_f32 v[242:243], v[242:243], 1.0 op_sel_hi:[1,0]
	v_rcp_f32_e32 v240, v240
	v_rcp_f32_e32 v241, v241
	v_rcp_f32_e32 v242, v242
	v_rcp_f32_e32 v243, v243
	v_pk_add_f32 v[240:241], v[240:241], 1.0 op_sel_hi:[1,0] neg_lo:[1,0] neg_hi:[1,0]
	v_pk_add_f32 v[242:243], v[242:243], 1.0 op_sel_hi:[1,0] neg_lo:[1,0] neg_hi:[1,0]
	v_pk_mul_f32 v[36:37], v[36:37], v[240:241]
	v_pk_mul_f32 v[38:39], v[38:39], v[242:243]
	v_cvt_pk_bf16_f32 v36, v36, v37
	v_cvt_pk_bf16_f32 v37, v38, v39
	global_store_dwordx2 v[246:247], v[36:37], off sc0 sc1
	v_pk_mul_f32 v[240:241], v[32:33], s[66:67]
	v_pk_mul_f32 v[242:243], v[34:35], s[66:67]
	v_pk_mul_f32 v[240:241], v[32:33], v[240:241]
	v_pk_mul_f32 v[242:243], v[34:35], v[242:243]
	v_pk_fma_f32 v[240:241], v[32:33], v[240:241], v[32:33]
	v_pk_fma_f32 v[242:243], v[34:35], v[242:243], v[34:35]
	v_pk_mul_f32 v[240:241], v[240:241], s[68:69]
	v_pk_mul_f32 v[242:243], v[242:243], s[68:69]
	v_pk_add_f32 v[240:241], v[240:241], v[240:241]
	v_pk_add_f32 v[242:243], v[242:243], v[242:243]
	v_pk_mul_f32 v[240:241], v[240:241], s[70:71]
	v_pk_mul_f32 v[242:243], v[242:243], s[70:71]
	v_exp_f32_e32 v240, v240
	v_exp_f32_e32 v241, v241
	v_exp_f32_e32 v242, v242
	v_exp_f32_e32 v243, v243
	v_pk_add_f32 v[240:241], v[240:241], 1.0 op_sel_hi:[1,0]
	v_pk_add_f32 v[242:243], v[242:243], 1.0 op_sel_hi:[1,0]
	v_rcp_f32_e32 v240, v240
	v_rcp_f32_e32 v241, v241
	v_rcp_f32_e32 v242, v242
	v_rcp_f32_e32 v243, v243
	v_pk_add_f32 v[240:241], v[240:241], 1.0 op_sel_hi:[1,0] neg_lo:[1,0] neg_hi:[1,0]
	v_pk_add_f32 v[242:243], v[242:243], 1.0 op_sel_hi:[1,0] neg_lo:[1,0] neg_hi:[1,0]
	v_pk_mul_f32 v[32:33], v[32:33], v[240:241]
	v_pk_mul_f32 v[34:35], v[34:35], v[242:243]
	v_cvt_pk_bf16_f32 v32, v32, v33
	v_cvt_pk_bf16_f32 v33, v34, v35
	global_store_dwordx2 v[246:247], v[32:33], off offset:512 sc0 sc1
	v_lshl_add_u64 v[250:251], v[250:251], 0, s[98:99]
	v_lshl_add_u64 v[246:247], v[246:247], 0, s[98:99]
	v_pk_mul_f32 v[240:241], v[28:29], s[66:67]
	v_pk_mul_f32 v[242:243], v[30:31], s[66:67]
	v_pk_mul_f32 v[240:241], v[28:29], v[240:241]
	v_pk_mul_f32 v[242:243], v[30:31], v[242:243]
	v_pk_fma_f32 v[240:241], v[28:29], v[240:241], v[28:29]
	v_pk_fma_f32 v[242:243], v[30:31], v[242:243], v[30:31]
	v_pk_mul_f32 v[240:241], v[240:241], s[68:69]
	v_pk_mul_f32 v[242:243], v[242:243], s[68:69]
	v_pk_add_f32 v[240:241], v[240:241], v[240:241]
	v_pk_add_f32 v[242:243], v[242:243], v[242:243]
	v_pk_mul_f32 v[240:241], v[240:241], s[70:71]
	v_pk_mul_f32 v[242:243], v[242:243], s[70:71]
	v_exp_f32_e32 v240, v240
	v_exp_f32_e32 v241, v241
	v_exp_f32_e32 v242, v242
	v_exp_f32_e32 v243, v243
	v_pk_add_f32 v[240:241], v[240:241], 1.0 op_sel_hi:[1,0]
	v_pk_add_f32 v[242:243], v[242:243], 1.0 op_sel_hi:[1,0]
	v_rcp_f32_e32 v240, v240
	v_rcp_f32_e32 v241, v241
	v_rcp_f32_e32 v242, v242
	v_rcp_f32_e32 v243, v243
	v_pk_add_f32 v[240:241], v[240:241], 1.0 op_sel_hi:[1,0] neg_lo:[1,0] neg_hi:[1,0]
	v_pk_add_f32 v[242:243], v[242:243], 1.0 op_sel_hi:[1,0] neg_lo:[1,0] neg_hi:[1,0]
	v_pk_mul_f32 v[28:29], v[28:29], v[240:241]
; __device__ __forceinline__ unsigned cvt_pk_bf16(float lo, float hi) { const f32x2_t v = {lo, hi}; const bf16x2_t b = __builtin_convertvector(v, bf16x2_t); return __builtin_bit_cast(unsigned, b); }
; __device__ __forceinline__ float gelu_tanh(float y) { const float u = 0.7978845608028654f * (y + 0.044715f * y * y * y); return y * (1.0f - __builtin_amdgcn_rcpf(1.0f + __expf(2.0f * u))); }
;     __device__ __forceinline__ void operator()(const Acc& acc, const Unit& u, int wr, int wc, int fr, int fq) const {
;     ...
;             for (int m = 0; m < 4; ++m) { const int crow = u.pm * 256 + ai * 128 + wr * 64 + m * 16 + fr;
; #pragma unroll
;                 for (int bj = 0; bj < 2; ++bj)
; #pragma unroll
;                     for (int n = 0; n < 2; ++n) { const int col = bj * 128 + wc * 32 + n * 16 + fq * 4, t = col >> 4, cp = col & 15; const f32x4 v = acc[ai][bj][m][n];
;                         *(u32x2*)(Z + ((size_t)crow * 16 + t) * 256 + u.z * 16 + cp) = (u32x2){cvt_pk_bf16(gelu_tanh(v[0]), gelu_tanh(v[1])), cvt_pk_bf16(gelu_tanh(v[2]), gelu_tanh(v[3]))}; } }
	v_pk_mul_f32 v[30:31], v[30:31], v[242:243]
	v_cvt_pk_bf16_f32 v28, v28, v29
	v_cvt_pk_bf16_f32 v29, v30, v31
	global_store_dwordx2 v[250:251], v[28:29], off sc0 sc1
	v_pk_mul_f32 v[240:241], v[24:25], s[66:67]
	v_pk_mul_f32 v[242:243], v[26:27], s[66:67]
	v_pk_mul_f32 v[240:241], v[24:25], v[240:241]
	v_pk_mul_f32 v[242:243], v[26:27], v[242:243]
	v_pk_fma_f32 v[240:241], v[24:25], v[240:241], v[24:25]
	v_pk_fma_f32 v[242:243], v[26:27], v[242:243], v[26:27]
	v_pk_mul_f32 v[240:241], v[240:241], s[68:69]
	v_pk_mul_f32 v[242:243], v[242:243], s[68:69]
	v_pk_add_f32 v[240:241], v[240:241], v[240:241]
	v_pk_add_f32 v[242:243], v[242:243], v[242:243]
	v_pk_mul_f32 v[240:241], v[240:241], s[70:71]
	v_pk_mul_f32 v[242:243], v[242:243], s[70:71]
	v_exp_f32_e32 v240, v240
	v_exp_f32_e32 v241, v241
	v_exp_f32_e32 v242, v242
	v_exp_f32_e32 v243, v243
	v_pk_add_f32 v[240:241], v[240:241], 1.0 op_sel_hi:[1,0]
	v_pk_add_f32 v[242:243], v[242:243], 1.0 op_sel_hi:[1,0]
	v_rcp_f32_e32 v240, v240
	v_rcp_f32_e32 v241, v241
	v_rcp_f32_e32 v242, v242
	v_rcp_f32_e32 v243, v243
	v_pk_add_f32 v[240:241], v[240:241], 1.0 op_sel_hi:[1,0] neg_lo:[1,0] neg_hi:[1,0]
	v_pk_add_f32 v[242:243], v[242:243], 1.0 op_sel_hi:[1,0] neg_lo:[1,0] neg_hi:[1,0]
	v_pk_mul_f32 v[24:25], v[24:25], v[240:241]
	v_pk_mul_f32 v[26:27], v[26:27], v[242:243]
	v_cvt_pk_bf16_f32 v24, v24, v25
	v_cvt_pk_bf16_f32 v25, v26, v27
	global_store_dwordx2 v[250:251], v[24:25], off offset:512 sc0 sc1
	v_pk_mul_f32 v[240:241], v[20:21], s[66:67]
	v_pk_mul_f32 v[242:243], v[22:23], s[66:67]
	v_pk_mul_f32 v[240:241], v[20:21], v[240:241]
	v_pk_mul_f32 v[242:243], v[22:23], v[242:243]
	v_pk_fma_f32 v[240:241], v[20:21], v[240:241], v[20:21]
	v_pk_fma_f32 v[242:243], v[22:23], v[242:243], v[22:23]
	v_pk_mul_f32 v[240:241], v[240:241], s[68:69]
	v_pk_mul_f32 v[242:243], v[242:243], s[68:69]
	v_pk_add_f32 v[240:241], v[240:241], v[240:241]
	v_pk_add_f32 v[242:243], v[242:243], v[242:243]
	v_pk_mul_f32 v[240:241], v[240:241], s[70:71]
	v_pk_mul_f32 v[242:243], v[242:243], s[70:71]
	v_exp_f32_e32 v240, v240
	v_exp_f32_e32 v241, v241
	v_exp_f32_e32 v242, v242
	v_exp_f32_e32 v243, v243
	v_pk_add_f32 v[240:241], v[240:241], 1.0 op_sel_hi:[1,0]
	v_pk_add_f32 v[242:243], v[242:243], 1.0 op_sel_hi:[1,0]
	v_rcp_f32_e32 v240, v240
	v_rcp_f32_e32 v241, v241
	v_rcp_f32_e32 v242, v242
	v_rcp_f32_e32 v243, v243
	v_pk_add_f32 v[240:241], v[240:241], 1.0 op_sel_hi:[1,0] neg_lo:[1,0] neg_hi:[1,0]
	v_pk_add_f32 v[242:243], v[242:243], 1.0 op_sel_hi:[1,0] neg_lo:[1,0] neg_hi:[1,0]
	v_pk_mul_f32 v[20:21], v[20:21], v[240:241]
	v_pk_mul_f32 v[22:23], v[22:23], v[242:243]
	v_cvt_pk_bf16_f32 v20, v20, v21
	v_cvt_pk_bf16_f32 v21, v22, v23
	global_store_dwordx2 v[246:247], v[20:21], off sc0 sc1
	v_pk_mul_f32 v[240:241], v[16:17], s[66:67]
	v_pk_mul_f32 v[242:243], v[18:19], s[66:67]
	v_pk_mul_f32 v[240:241], v[16:17], v[240:241]
	v_pk_mul_f32 v[242:243], v[18:19], v[242:243]
	v_pk_fma_f32 v[240:241], v[16:17], v[240:241], v[16:17]
	v_pk_fma_f32 v[242:243], v[18:19], v[242:243], v[18:19]
	v_pk_mul_f32 v[240:241], v[240:241], s[68:69]
	v_pk_mul_f32 v[242:243], v[242:243], s[68:69]
	v_pk_add_f32 v[240:241], v[240:241], v[240:241]
	v_pk_add_f32 v[242:243], v[242:243], v[242:243]
	v_pk_mul_f32 v[240:241], v[240:241], s[70:71]
	v_pk_mul_f32 v[242:243], v[242:243], s[70:71]
	v_exp_f32_e32 v240, v240
	v_exp_f32_e32 v241, v241
	v_exp_f32_e32 v242, v242
	v_exp_f32_e32 v243, v243
	v_pk_add_f32 v[240:241], v[240:241], 1.0 op_sel_hi:[1,0]
	v_pk_add_f32 v[242:243], v[242:243], 1.0 op_sel_hi:[1,0]
	v_rcp_f32_e32 v240, v240
	v_rcp_f32_e32 v241, v241
	v_rcp_f32_e32 v242, v242
	v_rcp_f32_e32 v243, v243
	v_pk_add_f32 v[240:241], v[240:241], 1.0 op_sel_hi:[1,0] neg_lo:[1,0] neg_hi:[1,0]
	v_pk_add_f32 v[242:243], v[242:243], 1.0 op_sel_hi:[1,0] neg_lo:[1,0] neg_hi:[1,0]
	v_pk_mul_f32 v[16:17], v[16:17], v[240:241]
	v_pk_mul_f32 v[18:19], v[18:19], v[242:243]
	v_cvt_pk_bf16_f32 v16, v16, v17
	v_cvt_pk_bf16_f32 v17, v18, v19
	global_store_dwordx2 v[246:247], v[16:17], off offset:512 sc0 sc1
	v_lshl_add_u64 v[250:251], v[250:251], 0, s[98:99]
	v_lshl_add_u64 v[246:247], v[246:247], 0, s[98:99]
	v_pk_mul_f32 v[240:241], v[12:13], s[66:67]
	v_pk_mul_f32 v[242:243], v[14:15], s[66:67]
	v_pk_mul_f32 v[240:241], v[12:13], v[240:241]
	v_pk_mul_f32 v[242:243], v[14:15], v[242:243]
	v_pk_fma_f32 v[240:241], v[12:13], v[240:241], v[12:13]
	v_pk_fma_f32 v[242:243], v[14:15], v[242:243], v[14:15]
	v_pk_mul_f32 v[240:241], v[240:241], s[68:69]
	v_pk_mul_f32 v[242:243], v[242:243], s[68:69]
	v_pk_add_f32 v[240:241], v[240:241], v[240:241]
	v_pk_add_f32 v[242:243], v[242:243], v[242:243]
; __device__ __forceinline__ unsigned cvt_pk_bf16(float lo, float hi) { const f32x2_t v = {lo, hi}; const bf16x2_t b = __builtin_convertvector(v, bf16x2_t); return __builtin_bit_cast(unsigned, b); }
; __device__ __forceinline__ float gelu_tanh(float y) { const float u = 0.7978845608028654f * (y + 0.044715f * y * y * y); return y * (1.0f - __builtin_amdgcn_rcpf(1.0f + __expf(2.0f * u))); }
;     __device__ __forceinline__ void operator()(const Acc& acc, const Unit& u, int wr, int wc, int fr, int fq) const {
;     ...
;             for (int m = 0; m < 4; ++m) { const int crow = u.pm * 256 + ai * 128 + wr * 64 + m * 16 + fr;
; #pragma unroll
;                 for (int bj = 0; bj < 2; ++bj)
; #pragma unroll
;                     for (int n = 0; n < 2; ++n) { const int col = bj * 128 + wc * 32 + n * 16 + fq * 4, t = col >> 4, cp = col & 15; const f32x4 v = acc[ai][bj][m][n];
;                         *(u32x2*)(Z + ((size_t)crow * 16 + t) * 256 + u.z * 16 + cp) = (u32x2){cvt_pk_bf16(gelu_tanh(v[0]), gelu_tanh(v[1])), cvt_pk_bf16(gelu_tanh(v[2]), gelu_tanh(v[3]))}; } }
	v_pk_mul_f32 v[240:241], v[240:241], s[70:71]
	v_pk_mul_f32 v[242:243], v[242:243], s[70:71]
	v_exp_f32_e32 v240, v240
	v_exp_f32_e32 v241, v241
	v_exp_f32_e32 v242, v242
	v_exp_f32_e32 v243, v243
	v_pk_add_f32 v[240:241], v[240:241], 1.0 op_sel_hi:[1,0]
	v_pk_add_f32 v[242:243], v[242:243], 1.0 op_sel_hi:[1,0]
	v_rcp_f32_e32 v240, v240
	v_rcp_f32_e32 v241, v241
	v_rcp_f32_e32 v242, v242
	v_rcp_f32_e32 v243, v243
	v_pk_add_f32 v[240:241], v[240:241], 1.0 op_sel_hi:[1,0] neg_lo:[1,0] neg_hi:[1,0]
	v_pk_add_f32 v[242:243], v[242:243], 1.0 op_sel_hi:[1,0] neg_lo:[1,0] neg_hi:[1,0]
	v_pk_mul_f32 v[12:13], v[12:13], v[240:241]
	v_pk_mul_f32 v[14:15], v[14:15], v[242:243]
	v_cvt_pk_bf16_f32 v12, v12, v13
	v_cvt_pk_bf16_f32 v13, v14, v15
	global_store_dwordx2 v[250:251], v[12:13], off sc0 sc1
	v_pk_mul_f32 v[240:241], v[8:9], s[66:67]
	v_pk_mul_f32 v[242:243], v[10:11], s[66:67]
	v_pk_mul_f32 v[240:241], v[8:9], v[240:241]
	v_pk_mul_f32 v[242:243], v[10:11], v[242:243]
	v_pk_fma_f32 v[240:241], v[8:9], v[240:241], v[8:9]
	v_pk_fma_f32 v[242:243], v[10:11], v[242:243], v[10:11]
	v_pk_mul_f32 v[240:241], v[240:241], s[68:69]
	v_pk_mul_f32 v[242:243], v[242:243], s[68:69]
	v_pk_add_f32 v[240:241], v[240:241], v[240:241]
	v_pk_add_f32 v[242:243], v[242:243], v[242:243]
	v_pk_mul_f32 v[240:241], v[240:241], s[70:71]
	v_pk_mul_f32 v[242:243], v[242:243], s[70:71]
	v_exp_f32_e32 v240, v240
	v_exp_f32_e32 v241, v241
	v_exp_f32_e32 v242, v242
	v_exp_f32_e32 v243, v243
	v_pk_add_f32 v[240:241], v[240:241], 1.0 op_sel_hi:[1,0]
	v_pk_add_f32 v[242:243], v[242:243], 1.0 op_sel_hi:[1,0]
	v_rcp_f32_e32 v240, v240
	v_rcp_f32_e32 v241, v241
	v_rcp_f32_e32 v242, v242
	v_rcp_f32_e32 v243, v243
	v_pk_add_f32 v[240:241], v[240:241], 1.0 op_sel_hi:[1,0] neg_lo:[1,0] neg_hi:[1,0]
	v_pk_add_f32 v[242:243], v[242:243], 1.0 op_sel_hi:[1,0] neg_lo:[1,0] neg_hi:[1,0]
	v_pk_mul_f32 v[8:9], v[8:9], v[240:241]
	v_pk_mul_f32 v[10:11], v[10:11], v[242:243]
	v_cvt_pk_bf16_f32 v8, v8, v9
	v_cvt_pk_bf16_f32 v9, v10, v11
	global_store_dwordx2 v[250:251], v[8:9], off offset:512 sc0 sc1
	v_pk_mul_f32 v[240:241], v[4:5], s[66:67]
	v_pk_mul_f32 v[242:243], v[6:7], s[66:67]
	v_pk_mul_f32 v[240:241], v[4:5], v[240:241]
	v_pk_mul_f32 v[242:243], v[6:7], v[242:243]
	v_pk_fma_f32 v[240:241], v[4:5], v[240:241], v[4:5]
	v_pk_fma_f32 v[242:243], v[6:7], v[242:243], v[6:7]
	v_pk_mul_f32 v[240:241], v[240:241], s[68:69]
	v_pk_mul_f32 v[242:243], v[242:243], s[68:69]
	v_pk_add_f32 v[240:241], v[240:241], v[240:241]
	v_pk_add_f32 v[242:243], v[242:243], v[242:243]
	v_pk_mul_f32 v[240:241], v[240:241], s[70:71]
	v_pk_mul_f32 v[242:243], v[242:243], s[70:71]
	v_exp_f32_e32 v240, v240
	v_exp_f32_e32 v241, v241
	v_exp_f32_e32 v242, v242
	v_exp_f32_e32 v243, v243
	v_pk_add_f32 v[240:241], v[240:241], 1.0 op_sel_hi:[1,0]
	v_pk_add_f32 v[242:243], v[242:243], 1.0 op_sel_hi:[1,0]
	v_rcp_f32_e32 v240, v240
	v_rcp_f32_e32 v241, v241
	v_rcp_f32_e32 v242, v242
	v_rcp_f32_e32 v243, v243
	v_pk_add_f32 v[240:241], v[240:241], 1.0 op_sel_hi:[1,0] neg_lo:[1,0] neg_hi:[1,0]
	v_pk_add_f32 v[242:243], v[242:243], 1.0 op_sel_hi:[1,0] neg_lo:[1,0] neg_hi:[1,0]
	v_pk_mul_f32 v[4:5], v[4:5], v[240:241]
	v_pk_mul_f32 v[6:7], v[6:7], v[242:243]
	v_cvt_pk_bf16_f32 v4, v4, v5
	v_cvt_pk_bf16_f32 v5, v6, v7
	global_store_dwordx2 v[246:247], v[4:5], off sc0 sc1
	v_pk_mul_f32 v[240:241], v[0:1], s[66:67]
	v_pk_mul_f32 v[242:243], v[2:3], s[66:67]
	v_pk_mul_f32 v[240:241], v[0:1], v[240:241]
	v_pk_mul_f32 v[242:243], v[2:3], v[242:243]
	v_pk_fma_f32 v[240:241], v[0:1], v[240:241], v[0:1]
	v_pk_fma_f32 v[242:243], v[2:3], v[242:243], v[2:3]
	v_pk_mul_f32 v[240:241], v[240:241], s[68:69]
	v_pk_mul_f32 v[242:243], v[242:243], s[68:69]
	v_pk_add_f32 v[240:241], v[240:241], v[240:241]
	v_pk_add_f32 v[242:243], v[242:243], v[242:243]
	v_pk_mul_f32 v[240:241], v[240:241], s[70:71]
	v_pk_mul_f32 v[242:243], v[242:243], s[70:71]
	v_exp_f32_e32 v240, v240
	v_exp_f32_e32 v241, v241
	v_exp_f32_e32 v242, v242
	v_exp_f32_e32 v243, v243
	v_pk_add_f32 v[240:241], v[240:241], 1.0 op_sel_hi:[1,0]
	v_pk_add_f32 v[242:243], v[242:243], 1.0 op_sel_hi:[1,0]
	v_rcp_f32_e32 v240, v240
	v_rcp_f32_e32 v241, v241
	v_rcp_f32_e32 v242, v242
	v_rcp_f32_e32 v243, v243
	v_pk_add_f32 v[240:241], v[240:241], 1.0 op_sel_hi:[1,0] neg_lo:[1,0] neg_hi:[1,0]
	v_pk_add_f32 v[242:243], v[242:243], 1.0 op_sel_hi:[1,0] neg_lo:[1,0] neg_hi:[1,0]
	v_pk_mul_f32 v[0:1], v[0:1], v[240:241]
	v_pk_mul_f32 v[2:3], v[2:3], v[242:243]
	v_cvt_pk_bf16_f32 v0, v0, v1
	v_cvt_pk_bf16_f32 v1, v2, v3
	global_store_dwordx2 v[246:247], v[0:1], off offset:512 sc0 sc1
	s_waitcnt vmcnt(0)
	s_barrier
